# hot-first chain: P7 processes the M-group whose H2 rows P5 wrote last first, P8 then starts with the group P7 wrote last (P7 order swapped, P8 natural)
# speedup vs baseline: 1.0025x; 1.0025x over previous
;     __device__ __forceinline__ bool next(int i, Unit& u) const { if (!base.next(i >> 1, u)) return false; if (i & 1) { u.pm += 64; u.pn += 8; } return true; }
; #define PG8_BAR __builtin_amdgcn_s_barrier()
;     __device__ bool next(int i, Unit& u) const {
;         const long L = (long)i * G + c; if (L >= nwg) return false;
;         int wgid = (int)L; { const int q = nwg / NXCD, r = nwg % NXCD, xcd = wgid % NXCD, off = wgid / NXCD; wgid = (xcd < r ? xcd * (q + 1) : r * (q + 1) + (xcd - r) * q) + off; }
;         const int nig = WG * nN, gid = wgid / nig, fm = gid * WG, gsz = (nM - fm) < WG ? (nM - fm) : WG;
;         u.pm = fm + ((wgid % nig) % gsz); u.pn = (wgid % nig) / gsz; return true;
; template <class Epi, class Sched, bool ALIGN_EPI = false, bool SP2 = false>
; __device__ __forceinline__ void gemm_phase(PG8_LAS unsigned char* lds, const Gemm g, const Sched& S, const Epi& E) {
;     ...
;     for (int i = 0; i < 2; ++i) { int R, C; stage_rc(tid * 16 + i * 8192, R, C); const int Rb = Epi::PERM ? ((R & ~31) + perm32(R & 31)) : R;
;         voffA[i] = (unsigned)(R * K + C) * 2u; voffB[i] = (unsigned)(Rb * K + C) * 2u; }
;     const size_t kstep = (size_t)(BK * 2);
;     const size_t hstep = (size_t)HALF * K * 2;
;     const size_t tstep = 2 * hstep;
;     const unsigned ldsw = (unsigned)wid * 1024u;
;     const int aoff = lds_byte(wr * 64 + fr, fq * 8), boff = lds_byte(wc * 32 + fr, fq * 8);
;     ...
;     Unit cur, nxt; int ui = 0;
;     if (!S.next(0, cur)) return;
;     f32x4 acc[2][2][4][2];
; #pragma unroll
;     for (int a = 0; a < 2; ++a)
; #pragma unroll
;         for (int b = 0; b < 2; ++b)
; #pragma unroll
;             for (int m = 0; m < 4; ++m)
; #pragma unroll
;                 for (int n = 0; n < 2; ++n) acc[a][b][m][n] = (f32x4){0.f, 0.f, 0.f, 0.f};
;     bf16x8 At[4][2], B0[2][2], B1[2][2];
;     const char* cA = (const char*)g.A + (size_t)cur.pm * tstep; const char* cB = (const char*)g.Bt + (size_t)cur.pn * tstep;
;     S.a_ready(cur);
;     if constexpr (SP2) {
;         PG8_STAGE(PG8_SB(0, 0), cB, voffB); PG8_STAGE(PG8_SB(0, 1), cB + hstep, voffB); PG8_STAGE(PG8_SA(0, 0), cA, voffA); PG8_STAGE(PG8_SA(0, 1), cA + hstep, voffA);
;         if (wr == 1) PG8_BAR;
.LBB0_982:
	v_ashrrev_i32_e32 v1, 31, v8
	v_lshrrev_b32_e32 v1, 26, v1
	v_add_u32_e32 v1, v8, v1
	v_ashrrev_i32_e32 v9, 6, v1
	v_bfe_i32 v1, v8, 27, 1
	v_lshlrev_b32_e32 v0, 4, v8
	v_lshrrev_b32_e32 v1, 22, v1
	v_add_u32_e32 v1, v0, v1
	v_and_b32_e32 v1, 0xfffffc00, v1
	v_sub_u32_e32 v1, v0, v1
	v_lshrrev_b32_e32 v2, 4, v1
	v_bitop3_b32 v1, v2, v1, 32 bitop3:0x6c
	v_ashrrev_i32_e32 v3, 31, v1
	v_lshrrev_b32_e32 v3, 26, v3
	v_add_u32_e32 v3, v1, v3
	v_lshlrev_b32_e32 v2, 3, v9
	v_ashrrev_i32_e32 v10, 6, v3
	v_and_b32_e32 v3, 0xc0, v3
	v_and_b32_e32 v2, -16, v2
	v_sub_u32_e32 v1, v1, v3
	v_mov_b32_e32 v3, 1
	v_add_u32_e32 v2, v10, v2
	v_ashrrev_i16_sdwa v1, v3, sext(v1) dst_sel:DWORD dst_unused:UNUSED_PAD src0_sel:DWORD src1_sel:BYTE_0
	v_lshlrev_b32_e32 v4, 5, v9
	v_bfe_i32 v11, v1, 0, 16
	v_lshlrev_b32_e32 v1, 1, v2
	v_lshrrev_b32_e32 v5, 2, v2
	v_and_b32_e32 v6, 3, v10
	s_mov_b32 s3, 0xfffe0
	v_and_b32_e32 v4, 32, v4
	v_and_b32_e32 v1, 24, v1
	v_and_b32_e32 v5, 4, v5
	v_and_or_b32 v6, v2, s3, v6
	v_or3_b32 v1, v6, v5, v1
	v_add_lshl_u32 v4, v4, v11, 1
	v_add_u32_e32 v0, 0x2000, v0
	v_lshl_add_u32 v146, v1, 12, v4
	v_ashrrev_i32_e32 v1, 31, v0
	v_lshrrev_b32_e32 v1, 22, v1
	v_add_u32_e32 v1, v0, v1
	v_ashrrev_i32_e32 v12, 10, v1
	v_mul_i32_i24_e32 v1, 0x400, v12
	v_sub_u32_e32 v0, v0, v1
	v_lshrrev_b32_e32 v1, 4, v0
	v_bitop3_b32 v0, v1, v0, 32 bitop3:0x6c
	v_lshl_add_u32 v144, v2, 12, v4
	v_ashrrev_i32_e32 v2, 31, v0
	v_lshrrev_b32_e32 v2, 26, v2
	v_add_u32_e32 v2, v0, v2
	v_lshlrev_b32_e32 v1, 3, v12
	v_ashrrev_i32_e32 v13, 6, v2
	v_and_b32_e32 v2, 0xc0, v2
	s_ashr_i32 s2, s5, 3
	v_and_b32_e32 v1, -16, v1
	v_sub_u32_e32 v0, v0, v2
	v_add_u32_e32 v1, v13, v1
	v_ashrrev_i16_sdwa v0, v3, sext(v0) dst_sel:DWORD dst_unused:UNUSED_PAD src0_sel:DWORD src1_sel:BYTE_0
	v_and_b32_e32 v3, 3, v13
	s_add_i32 s2, s6, s2
	v_and_or_b32 v3, v1, s3, v3
	s_ashr_i32 s3, s2, 31
	s_lshr_b32 s3, s3, 25
	s_add_i32 s3, s2, s3
	s_ashr_i32 s6, s3, 7
	s_and_b32 s3, s3, 0xffffff80
	s_sub_i32 s3, s2, s3
	s_bfe_i32 s2, s3, 0x80000
	s_bfe_u32 s2, s2, 0x2000d
	s_add_i32 s7, s3, s2
	s_bfe_i32 s2, s7, 0x80000
	s_and_b32 s7, s7, 0xfc
	s_sub_i32 s3, s3, s7
	s_lshl_b32 s6, s6, 2
	s_xor_b32 s6, s6, 4
	s_sext_i32_i16 s2, s2
	s_sext_i32_i8 s3, s3
	s_lshr_b32 s2, s2, 2
	s_add_i32 s22, s6, s3
	s_ashr_i32 s10, s4, 6
	s_ashr_i32 s23, s22, 31
	s_bfe_i64 s[12:13], s[2:3], 0x100000
	s_ashr_i32 s5, s4, 8
	s_lshl_b32 s31, s10, 10
	s_lshl_b64 s[6:7], s[22:23], 20
	s_lshl_b64 s[12:13], s[12:13], 20
	v_readlane_b32 s14, v236, 52
	v_readlane_b32 s15, v236, 53
	s_add_u32 s26, s14, s12
	v_lshlrev_b32_e32 v4, 5, v12
	v_bfe_i32 v14, v0, 0, 16
	v_lshlrev_b32_e32 v0, 1, v1
	v_lshrrev_b32_e32 v2, 2, v1
	s_addc_u32 s27, s15, s13
	s_add_i32 s23, s31, 0
	v_and_b32_e32 v4, 32, v4
	v_and_b32_e32 v0, 24, v0
	v_and_b32_e32 v2, 4, v2
	s_add_i32 m0, s23, 0x10000
	v_or3_b32 v0, v3, v2, v0
	v_add_lshl_u32 v2, v4, v14, 1
	global_load_lds_dwordx4 v146, s[26:27]
	s_add_i32 m0, s23, 0x12000
	v_lshl_add_u32 v150, v0, 12, v2
	s_add_u32 s12, s26, 0x80000
	global_load_lds_dwordx4 v150, s[26:27]
	s_addc_u32 s13, s27, 0
	s_add_i32 m0, s23, 0x14000
	v_lshl_add_u32 v148, v1, 12, v2
	global_load_lds_dwordx4 v146, s[12:13]
	s_add_i32 m0, s23, 0x16000
	s_add_u32 s24, s8, s6
	s_addc_u32 s25, s9, s7
	s_add_i32 s33, s23, 0x2000
	global_load_lds_dwordx4 v150, s[12:13]
	s_mov_b32 m0, s23
	s_add_u32 s6, s24, 0x80000
	global_load_lds_dwordx4 v144, s[24:25]
	s_mov_b32 m0, s33
	s_addc_u32 s7, s25, 0
	s_add_i32 s34, s23, 0x4000
	global_load_lds_dwordx4 v148, s[24:25]
	s_mov_b32 m0, s34
	s_add_i32 s35, s23, 0x6000
	global_load_lds_dwordx4 v144, s[6:7]
	s_mov_b32 m0, s35
	v_mov_b32_e32 v147, 0
	global_load_lds_dwordx4 v148, s[6:7]
	v_mov_b32_e32 v151, v147
	v_mov_b32_e32 v145, v147
	v_mov_b32_e32 v149, v147
	s_cmp_eq_u32 s5, 1
	s_mov_b32 s3, 0
	v_lshl_add_u64 v[6:7], s[26:27], 0, v[146:147]
	v_lshl_add_u64 v[4:5], s[26:27], 0, v[150:151]
	v_lshl_add_u64 v[0:1], s[24:25], 0, v[144:145]
	s_cselect_b64 s[6:7], -1, 0
	s_cmp_lg_u32 s5, 1
	v_lshl_add_u64 v[2:3], s[24:25], 0, v[148:149]
	s_cbranch_scc1 .LBB0_984
	s_barrier

;     __device__ __forceinline__ bool next(int i, Unit& u) const { if (!base.next(i >> 1, u)) return false; if (i & 1) { u.pm += 64; u.pn += 8; } return true; }
;     __device__ bool next(int i, Unit& u) const {
;         const long L = (long)i * G + c; if (L >= nwg) return false;
;         int wgid = (int)L; { const int q = nwg / NXCD, r = nwg % NXCD, xcd = wgid % NXCD, off = wgid / NXCD; wgid = (xcd < r ? xcd * (q + 1) : r * (q + 1) + (xcd - r) * q) + off; }
;         const int nig = WG * nN, gid = wgid / nig, fm = gid * WG, gsz = (nM - fm) < WG ? (nM - fm) : WG;
;         u.pm = fm + ((wgid % nig) % gsz); u.pn = (wgid % nig) / gsz; return true;
.LBB0_992:
	s_ashr_i32 s14, s16, 3
	s_add_i32 s14, s18, s14
	s_ashr_i32 s15, s14, 31
	s_lshr_b32 s15, s15, 25
	s_add_i32 s15, s14, s15
	s_ashr_i32 s16, s15, 7
	s_and_b32 s15, s15, 0xff80
	s_sub_i32 s14, s14, s15
	s_bfe_i32 s15, s14, 0x80000
	s_bfe_u32 s15, s15, 0x2000d
	s_add_i32 s15, s14, s15
	s_and_b32 s17, s15, 0xfc
	s_sub_i32 s14, s14, s17
	s_bfe_i32 s15, s15, 0x80000
	s_lshl_b32 s16, s16, 2
	s_xor_b32 s16, s16, 4
	s_sext_i32_i8 s14, s14
	s_sext_i32_i16 s15, s15
	s_add_i32 s14, s16, s14
	s_ashr_i32 s16, s15, 2
